# R7_CB: the six LDS fragments of a step are read together before the six MFMAs
# baseline (speedup 1.0000x reference)
; __device__ __forceinline__ bfr f2b(float f) { return (bfr)(cvtpk(f, f) & 0xffffu); }
; __device__ __forceinline__ float b2f(bfr b) { return __uint_as_float(((unsigned)b) << 16); }
; __device__ __forceinline__ void store4b(bfr* dst, f32x4 v) { uint2 u; u.x = pk2(v[0], v[1]); u.y = pk2(v[2], v[3]); *(uint2*)dst = u; }
; __device__ __forceinline__ void ph_r7_cb(const P& p, int win, char* smem) {
;     ...
;           const int cur = s & 1, nxt = cur ^ 1, c = c0 + s;
;           bf16x8 sh[2], sl[2], vt[2];
; #pragma unroll
;           for (int ks = 0; ks < 2; ks++) { sh[ks] = *(const bf16x8*)(Sh + (cur * 16 + l15) * CS + 32 * ks + 8 * q4); sl[ks] = *(const bf16x8*)(Sl + (cur * 16 + l15) * CS + 32 * ks + 8 * q4);
;             vt[ks] = *(const bf16x8*)(VT + (cur * 16 + l15) * CS + 32 * ks + 8 * q4); }
;           f32x4 a1 = f32x4{0.f, 0.f, 0.f, 0.f}, a2 = a1;
; #pragma unroll
;           for (int ks = 0; ks < 2; ks++) { a1 = __builtin_amdgcn_mfma_f32_16x16x32_bf16(sh[ks], rb1[u][ks], a1, 0, 0, 0); a2 = __builtin_amdgcn_mfma_f32_16x16x32_bf16(vt[ks], rb2[u][ks], a2, 0, 0, 0); }
; #pragma unroll
;           for (int ks = 0; ks < 2; ks++) a1 = __builtin_amdgcn_mfma_f32_16x16x32_bf16(sl[ks], rb1[u][ks], a1, 0, 0, 0);
;           a1 = a1 + a2;
;           if (w < 4) {
; #pragma unroll
;             for (int jj = 0; jj < 4; jj++) { const bfr hi = f2b(a1[jj]); Sh[(nxt * 16 + 4 * q4 + jj) * CS + 16 * w + l15] = hi; Sl[(nxt * 16 + 4 * q4 + jj) * CS + 16 * w + l15] = f2b(a1[jj] - b2f(hi)); }
;           } else {
;             const int rowy = rowmap(d, b, 64 * c + 16 * (w - 4) + l15);
;             store4b(Y + (size_t)rowy * 1024 + h * 64 + rg * 16 + 4 * q4, a1);
.LBB0_148:
	ds_read_b128 v[188:191], v100 offset:9216
	ds_read_b128 v[192:195], v100
	ds_read_b128 v[196:199], v100 offset:64
	ds_read_b128 v[200:203], v100 offset:4608
	ds_read_b128 v[204:207], v100 offset:9280
	ds_read_b128 v[208:211], v100 offset:4672
	s_waitcnt vmcnt(16) lgkmcnt(0)
	v_add_u32_e32 v117, s56, v98
	v_mfma_f32_16x16x32_bf16 v[62:65], v[188:191], v[62:65], 0
	v_mfma_f32_16x16x32_bf16 v[118:121], v[192:195], v[58:61], 0
	v_mfma_f32_16x16x32_bf16 v[118:121], v[196:199], v[50:53], v[118:121]
	v_mfma_f32_16x16x32_bf16 v[58:61], v[200:203], v[58:61], v[118:121]
	v_mfma_f32_16x16x32_bf16 v[54:57], v[204:207], v[54:57], v[62:65]
	v_mfma_f32_16x16x32_bf16 v[58:61], v[208:211], v[50:53], v[58:61]
	s_nop 7
	s_nop 1
	v_pk_add_f32 v[50:51], v[60:61], v[56:57]
	v_pk_add_f32 v[52:53], v[58:59], v[54:55]
	s_and_saveexec_b64 s[46:47], s[42:43]
	s_xor_b64 s[46:47], exec, s[46:47]
	s_cbranch_execz .LBB0_150
	v_subrev_u32_e32 v54, 64, v117
	v_cmp_lt_i32_e32 vcc, s15, v54
	v_cvt_pk_bf16_f32 v52, v52, v53
	v_cvt_pk_bf16_f32 v53, v50, v51
	v_cndmask_b32_e32 v55, v176, v177, vcc
	v_add_u32_e32 v55, s50, v55
	v_add3_u32 v55, v55, v115, 64
	v_cndmask_b32_e64 v54, v55, v54, s[44:45]
	v_add_u32_e32 v54, s52, v54
	v_ashrrev_i32_e32 v55, 31, v54
	v_lshlrev_b64 v[54:55], 11, v[54:55]
	v_lshl_add_u64 v[54:55], v[82:83], 0, v[54:55]
	global_store_dwordx2 v[54:55], v[52:53], off

; __device__ __forceinline__ bfr f2b(float f) { return (bfr)(cvtpk(f, f) & 0xffffu); }
; __device__ __forceinline__ float b2f(bfr b) { return __uint_as_float(((unsigned)b) << 16); }
; __device__ __forceinline__ void store4b(bfr* dst, f32x4 v) { uint2 u; u.x = pk2(v[0], v[1]); u.y = pk2(v[2], v[3]); *(uint2*)dst = u; }
; __device__ __forceinline__ void ph_r7_cb(const P& p, int win, char* smem) {
;     ...
;           const int cur = s & 1, nxt = cur ^ 1, c = c0 + s;
;           bf16x8 sh[2], sl[2], vt[2];
; #pragma unroll
;           for (int ks = 0; ks < 2; ks++) { sh[ks] = *(const bf16x8*)(Sh + (cur * 16 + l15) * CS + 32 * ks + 8 * q4); sl[ks] = *(const bf16x8*)(Sl + (cur * 16 + l15) * CS + 32 * ks + 8 * q4);
;             vt[ks] = *(const bf16x8*)(VT + (cur * 16 + l15) * CS + 32 * ks + 8 * q4); }
;           f32x4 a1 = f32x4{0.f, 0.f, 0.f, 0.f}, a2 = a1;
; #pragma unroll
;           for (int ks = 0; ks < 2; ks++) { a1 = __builtin_amdgcn_mfma_f32_16x16x32_bf16(sh[ks], rb1[u][ks], a1, 0, 0, 0); a2 = __builtin_amdgcn_mfma_f32_16x16x32_bf16(vt[ks], rb2[u][ks], a2, 0, 0, 0); }
; #pragma unroll
;           for (int ks = 0; ks < 2; ks++) a1 = __builtin_amdgcn_mfma_f32_16x16x32_bf16(sl[ks], rb1[u][ks], a1, 0, 0, 0);
;           a1 = a1 + a2;
;           if (w < 4) {
; #pragma unroll
;             for (int jj = 0; jj < 4; jj++) { const bfr hi = f2b(a1[jj]); Sh[(nxt * 16 + 4 * q4 + jj) * CS + 16 * w + l15] = hi; Sl[(nxt * 16 + 4 * q4 + jj) * CS + 16 * w + l15] = f2b(a1[jj] - b2f(hi)); }
;           } else {
;             const int rowy = rowmap(d, b, 64 * c + 16 * (w - 4) + l15);
;             store4b(Y + (size_t)rowy * 1024 + h * 64 + rg * 16 + 4 * q4, a1);
;           }
;           if (s + 1 < 20) { VT[(nxt * 16 + 2 * vp) * CS + vtau] = (bfr)(rv[u] & 0xffff); VT[(nxt * 16 + 2 * vp + 1) * CS + vtau] = (bfr)(rv[u] >> 16); }
;           if (s + 4 < 20) CB_LOAD(u, s + 4)
;           __syncthreads();
.LBB0_152:
	s_or_b64 exec, exec, s[46:47]
	v_lshl_add_u64 v[86:87], v[84:85], 0, s[30:31]
	v_add_co_u32_e32 v50, vcc, 0x20000, v86
	v_add_u32_e32 v118, s56, v69
	s_nop 0
	v_addc_co_u32_e32 v51, vcc, 0, v87, vcc
	v_add_co_u32_e32 v54, vcc, 0x22000, v86
	s_waitcnt vmcnt(15)
	ds_write_b16 v102, v114 offset:11520
	ds_write_b16_d16_hi v89, v114 offset:11664
	v_addc_co_u32_e32 v55, vcc, 0, v87, vcc
	v_add_u32_e32 v114, 0x140, v118
	v_cmp_lt_i32_e32 vcc, s15, v114
	s_movk_i32 s28, 0xfec0
	s_lshl_b32 s46, s54, 1
	v_cndmask_b32_e32 v119, v176, v177, vcc
	v_add_u32_e32 v119, s50, v119
	v_add3_u32 v119, v119, v79, s28
	v_cndmask_b32_e64 v114, v119, v114, s[44:45]
	v_add_u32_e32 v120, s52, v114
	v_ashrrev_i32_e32 v121, 31, v120
	v_lshlrev_b64 v[120:121], 13, v[120:121]
	v_lshl_add_u64 v[120:121], s[38:39], 0, v[120:121]
	s_lshl_b32 s28, s53, 1
	v_lshl_add_u64 v[120:121], v[120:121], 0, s[28:29]
	s_mov_b32 s47, s29
	v_lshl_add_u64 v[120:121], v[120:121], 0, s[46:47]
	v_lshl_add_u64 v[120:121], v[120:121], 0, v[0:1]
	v_add_co_u32_e32 v120, vcc, s33, v120
	global_load_dwordx4 v[58:61], v[50:51], off
	s_nop 0
	global_load_dwordx4 v[50:53], v[50:51], off offset:64
	v_addc_co_u32_e32 v121, vcc, 0, v121, vcc
	global_load_dwordx4 v[62:65], v[54:55], off
	s_nop 0
	global_load_dwordx4 v[54:57], v[54:55], off offset:64
	s_nop 0
	global_load_dword v114, v[120:121], off
	s_waitcnt lgkmcnt(0)
	s_barrier
	ds_read_b128 v[188:191], v100 offset:2304
	ds_read_b128 v[192:195], v100 offset:2368
	ds_read_b128 v[196:199], v100 offset:6912
	ds_read_b128 v[200:203], v100 offset:6976
	ds_read_b128 v[204:207], v100 offset:11520
	ds_read_b128 v[208:211], v100 offset:11584
	s_waitcnt vmcnt(16) lgkmcnt(0)
	v_mfma_f32_16x16x32_bf16 v[120:123], v[188:191], v[42:45], 0
	v_mfma_f32_16x16x32_bf16 v[120:123], v[192:195], v[34:37], v[120:123]
	v_mfma_f32_16x16x32_bf16 v[42:45], v[196:199], v[42:45], v[120:123]
	v_mfma_f32_16x16x32_bf16 v[42:45], v[200:203], v[34:37], v[42:45]
	v_mfma_f32_16x16x32_bf16 v[34:37], v[204:207], v[46:49], 0
	v_mfma_f32_16x16x32_bf16 v[36:39], v[208:211], v[38:41], v[34:37]
	s_nop 7
	s_nop 1
	v_pk_add_f32 v[34:35], v[44:45], v[38:39]
	v_pk_add_f32 v[36:37], v[42:43], v[36:37]
	s_and_saveexec_b64 s[48:49], s[42:43]
	s_xor_b64 s[48:49], exec, s[48:49]
	s_cbranch_execz .LBB0_154
	v_cmp_lt_i32_e32 vcc, s15, v117
	v_cvt_pk_bf16_f32 v36, v36, v37
	v_cvt_pk_bf16_f32 v37, v34, v35
	v_cndmask_b32_e32 v38, v176, v177, vcc
	v_add3_u32 v38, s50, v38, v115
	v_cndmask_b32_e64 v38, v38, v117, s[44:45]
	v_add_u32_e32 v38, s52, v38
	v_ashrrev_i32_e32 v39, 31, v38
	v_lshlrev_b64 v[38:39], 11, v[38:39]
	v_lshl_add_u64 v[38:39], v[82:83], 0, v[38:39]
	global_store_dwordx2 v[38:39], v[36:37], off

; __device__ __forceinline__ bfr f2b(float f) { return (bfr)(cvtpk(f, f) & 0xffffu); }
; __device__ __forceinline__ float b2f(bfr b) { return __uint_as_float(((unsigned)b) << 16); }
; __device__ __forceinline__ void store4b(bfr* dst, f32x4 v) { uint2 u; u.x = pk2(v[0], v[1]); u.y = pk2(v[2], v[3]); *(uint2*)dst = u; }
; __device__ __forceinline__ void ph_r7_cb(const P& p, int win, char* smem) {
;     ...
;           const int cur = s & 1, nxt = cur ^ 1, c = c0 + s;
;           bf16x8 sh[2], sl[2], vt[2];
; #pragma unroll
;           for (int ks = 0; ks < 2; ks++) { sh[ks] = *(const bf16x8*)(Sh + (cur * 16 + l15) * CS + 32 * ks + 8 * q4); sl[ks] = *(const bf16x8*)(Sl + (cur * 16 + l15) * CS + 32 * ks + 8 * q4);
;             vt[ks] = *(const bf16x8*)(VT + (cur * 16 + l15) * CS + 32 * ks + 8 * q4); }
;           f32x4 a1 = f32x4{0.f, 0.f, 0.f, 0.f}, a2 = a1;
; #pragma unroll
;           for (int ks = 0; ks < 2; ks++) { a1 = __builtin_amdgcn_mfma_f32_16x16x32_bf16(sh[ks], rb1[u][ks], a1, 0, 0, 0); a2 = __builtin_amdgcn_mfma_f32_16x16x32_bf16(vt[ks], rb2[u][ks], a2, 0, 0, 0); }
; #pragma unroll
;           for (int ks = 0; ks < 2; ks++) a1 = __builtin_amdgcn_mfma_f32_16x16x32_bf16(sl[ks], rb1[u][ks], a1, 0, 0, 0);
;           a1 = a1 + a2;
;           if (w < 4) {
; #pragma unroll
;             for (int jj = 0; jj < 4; jj++) { const bfr hi = f2b(a1[jj]); Sh[(nxt * 16 + 4 * q4 + jj) * CS + 16 * w + l15] = hi; Sl[(nxt * 16 + 4 * q4 + jj) * CS + 16 * w + l15] = f2b(a1[jj] - b2f(hi)); }
;           } else {
;             const int rowy = rowmap(d, b, 64 * c + 16 * (w - 4) + l15);
;             store4b(Y + (size_t)rowy * 1024 + h * 64 + rg * 16 + 4 * q4, a1);
;           }
;           if (s + 1 < 20) { VT[(nxt * 16 + 2 * vp) * CS + vtau] = (bfr)(rv[u] & 0xffff); VT[(nxt * 16 + 2 * vp + 1) * CS + vtau] = (bfr)(rv[u] >> 16); }
;           if (s + 4 < 20) CB_LOAD(u, s + 4)
;           __syncthreads();
.LBB0_156:
	s_or_b64 exec, exec, s[48:49]
	v_add_co_u32_e32 v34, vcc, 0x28000, v86
	s_waitcnt vmcnt(15)
	ds_write_b16 v102, v81 offset:9216
	ds_write_b16_d16_hi v89, v81 offset:9360
	v_addc_co_u32_e32 v35, vcc, 0, v87, vcc
	v_add_co_u32_e32 v38, vcc, 0x2a000, v86
	v_add_u32_e32 v81, 0x180, v118
	s_nop 0
	v_addc_co_u32_e32 v39, vcc, 0, v87, vcc
	v_cmp_lt_i32_e32 vcc, s15, v81
	s_movk_i32 s47, 0xfe80
	global_load_dwordx4 v[42:45], v[34:35], off
	s_nop 0
	global_load_dwordx4 v[34:37], v[34:35], off offset:64
	v_cndmask_b32_e32 v119, v176, v177, vcc
	v_add_u32_e32 v119, s50, v119
	v_add3_u32 v119, v119, v79, s47
	v_cndmask_b32_e64 v81, v119, v81, s[44:45]
	v_add_u32_e32 v120, s52, v81
	v_ashrrev_i32_e32 v121, 31, v120
	v_lshlrev_b64 v[120:121], 13, v[120:121]
	v_lshl_add_u64 v[120:121], s[38:39], 0, v[120:121]
	v_lshl_add_u64 v[120:121], v[120:121], 0, s[28:29]
	s_mov_b32 s47, s29
	v_lshl_add_u64 v[120:121], v[120:121], 0, s[46:47]
	v_lshl_add_u64 v[120:121], v[120:121], 0, v[0:1]
	v_add_co_u32_e32 v120, vcc, s33, v120
	global_load_dwordx4 v[46:49], v[38:39], off
	s_nop 0
	global_load_dwordx4 v[38:41], v[38:39], off offset:64
	v_addc_co_u32_e32 v121, vcc, 0, v121, vcc
	global_load_dword v81, v[120:121], off
	s_waitcnt lgkmcnt(0)
	s_barrier
	ds_read_b128 v[188:191], v100
	ds_read_b128 v[192:195], v100 offset:64
	ds_read_b128 v[196:199], v100 offset:4608
	ds_read_b128 v[200:203], v100 offset:4672
	ds_read_b128 v[204:207], v100 offset:9216
	ds_read_b128 v[208:211], v100 offset:9280
	s_waitcnt vmcnt(16) lgkmcnt(0)
	v_mfma_f32_16x16x32_bf16 v[120:123], v[188:191], v[26:29], 0
	v_mfma_f32_16x16x32_bf16 v[120:123], v[192:195], v[18:21], v[120:123]
	v_mfma_f32_16x16x32_bf16 v[26:29], v[196:199], v[26:29], v[120:123]
	v_mfma_f32_16x16x32_bf16 v[26:29], v[200:203], v[18:21], v[26:29]
	v_mfma_f32_16x16x32_bf16 v[18:21], v[204:207], v[30:33], 0
	v_mfma_f32_16x16x32_bf16 v[20:23], v[208:211], v[22:25], v[18:21]
	s_nop 7
	s_nop 1
	v_pk_add_f32 v[18:19], v[28:29], v[22:23]
	v_pk_add_f32 v[20:21], v[26:27], v[20:21]
	s_and_saveexec_b64 s[48:49], s[42:43]
	s_xor_b64 s[48:49], exec, s[48:49]
	s_cbranch_execz .LBB0_158
	v_add3_u32 v22, v98, s56, 64
	v_cmp_lt_i32_e32 vcc, s15, v22
	s_movk_i32 s47, 0xffc0
	v_cvt_pk_bf16_f32 v20, v20, v21
	v_cndmask_b32_e32 v23, v176, v177, vcc
	v_add_u32_e32 v23, s50, v23
	v_add3_u32 v23, v23, v115, s47
	v_cndmask_b32_e64 v22, v23, v22, s[44:45]
	v_add_u32_e32 v22, s52, v22
	v_ashrrev_i32_e32 v23, 31, v22
	v_lshlrev_b64 v[22:23], 11, v[22:23]
	v_lshl_add_u64 v[22:23], v[82:83], 0, v[22:23]
	v_cvt_pk_bf16_f32 v21, v18, v19
	global_store_dwordx2 v[22:23], v[20:21], off

; __device__ __forceinline__ bfr f2b(float f) { return (bfr)(cvtpk(f, f) & 0xffffu); }
; __device__ __forceinline__ float b2f(bfr b) { return __uint_as_float(((unsigned)b) << 16); }
; __device__ __forceinline__ void store4b(bfr* dst, f32x4 v) { uint2 u; u.x = pk2(v[0], v[1]); u.y = pk2(v[2], v[3]); *(uint2*)dst = u; }
; __device__ __forceinline__ void ph_r7_cb(const P& p, int win, char* smem) {
;     ...
;           const int cur = s & 1, nxt = cur ^ 1, c = c0 + s;
;           bf16x8 sh[2], sl[2], vt[2];
; #pragma unroll
;           for (int ks = 0; ks < 2; ks++) { sh[ks] = *(const bf16x8*)(Sh + (cur * 16 + l15) * CS + 32 * ks + 8 * q4); sl[ks] = *(const bf16x8*)(Sl + (cur * 16 + l15) * CS + 32 * ks + 8 * q4);
;             vt[ks] = *(const bf16x8*)(VT + (cur * 16 + l15) * CS + 32 * ks + 8 * q4); }
;           f32x4 a1 = f32x4{0.f, 0.f, 0.f, 0.f}, a2 = a1;
; #pragma unroll
;           for (int ks = 0; ks < 2; ks++) { a1 = __builtin_amdgcn_mfma_f32_16x16x32_bf16(sh[ks], rb1[u][ks], a1, 0, 0, 0); a2 = __builtin_amdgcn_mfma_f32_16x16x32_bf16(vt[ks], rb2[u][ks], a2, 0, 0, 0); }
; #pragma unroll
;           for (int ks = 0; ks < 2; ks++) a1 = __builtin_amdgcn_mfma_f32_16x16x32_bf16(sl[ks], rb1[u][ks], a1, 0, 0, 0);
;           a1 = a1 + a2;
;           if (w < 4) {
; #pragma unroll
;             for (int jj = 0; jj < 4; jj++) { const bfr hi = f2b(a1[jj]); Sh[(nxt * 16 + 4 * q4 + jj) * CS + 16 * w + l15] = hi; Sl[(nxt * 16 + 4 * q4 + jj) * CS + 16 * w + l15] = f2b(a1[jj] - b2f(hi)); }
;           } else {
;             const int rowy = rowmap(d, b, 64 * c + 16 * (w - 4) + l15);
;             store4b(Y + (size_t)rowy * 1024 + h * 64 + rg * 16 + 4 * q4, a1);
;           }
;           if (s + 1 < 20) { VT[(nxt * 16 + 2 * vp) * CS + vtau] = (bfr)(rv[u] & 0xffff); VT[(nxt * 16 + 2 * vp + 1) * CS + vtau] = (bfr)(rv[u] >> 16); }
;           if (s + 4 < 20) CB_LOAD(u, s + 4)
;           __syncthreads();
.LBB0_160:
	s_or_b64 exec, exec, s[48:49]
	v_add_co_u32_e32 v18, vcc, 0x30000, v86
	s_waitcnt vmcnt(15)
	ds_write_b16 v102, v77 offset:11520
	ds_write_b16_d16_hi v89, v77 offset:11664
	v_addc_co_u32_e32 v19, vcc, 0, v87, vcc
	v_add_co_u32_e32 v22, vcc, 0x32000, v86
	v_add_u32_e32 v77, 0x1c0, v118
	s_nop 0
	v_addc_co_u32_e32 v23, vcc, 0, v87, vcc
	v_cmp_lt_i32_e32 vcc, s15, v77
	s_movk_i32 s47, 0xfe40
	global_load_dwordx4 v[26:29], v[18:19], off
	s_nop 0
	global_load_dwordx4 v[18:21], v[18:19], off offset:64
	v_cndmask_b32_e32 v118, v176, v177, vcc
	v_add_u32_e32 v118, s50, v118
	v_add3_u32 v118, v118, v79, s47
	v_cndmask_b32_e64 v77, v118, v77, s[44:45]
	v_add_u32_e32 v118, s52, v77
	v_ashrrev_i32_e32 v119, 31, v118
	v_lshlrev_b64 v[118:119], 13, v[118:119]
	v_lshl_add_u64 v[118:119], s[38:39], 0, v[118:119]
	v_lshl_add_u64 v[118:119], v[118:119], 0, s[28:29]
	s_mov_b32 s47, s29
	v_lshl_add_u64 v[118:119], v[118:119], 0, s[46:47]
	v_lshl_add_u64 v[118:119], v[118:119], 0, v[0:1]
	v_add_co_u32_e32 v118, vcc, s33, v118
	global_load_dwordx4 v[30:33], v[22:23], off
	s_nop 0
	global_load_dwordx4 v[22:25], v[22:23], off offset:64
	v_addc_co_u32_e32 v119, vcc, 0, v119, vcc
	global_load_dword v77, v[118:119], off
	s_waitcnt lgkmcnt(0)
	s_barrier
	ds_read_b128 v[188:191], v100 offset:2304
	ds_read_b128 v[192:195], v100 offset:2368
	ds_read_b128 v[196:199], v100 offset:6912
	ds_read_b128 v[200:203], v100 offset:6976
	ds_read_b128 v[204:207], v100 offset:11520
	ds_read_b128 v[208:211], v100 offset:11584
	s_waitcnt vmcnt(16) lgkmcnt(0)
	v_mfma_f32_16x16x32_bf16 v[118:121], v[188:191], v[10:13], 0
	v_mfma_f32_16x16x32_bf16 v[118:121], v[192:195], v[2:5], v[118:121]
	v_mfma_f32_16x16x32_bf16 v[10:13], v[196:199], v[10:13], v[118:121]
	v_mfma_f32_16x16x32_bf16 v[10:13], v[200:203], v[2:5], v[10:13]
	v_mfma_f32_16x16x32_bf16 v[2:5], v[204:207], v[14:17], 0
	v_mfma_f32_16x16x32_bf16 v[4:7], v[208:211], v[6:9], v[2:5]
	s_nop 7
	s_nop 1
	v_pk_add_f32 v[2:3], v[12:13], v[6:7]
	v_pk_add_f32 v[4:5], v[10:11], v[4:5]
	s_and_saveexec_b64 s[48:49], s[42:43]
	s_xor_b64 s[48:49], exec, s[48:49]
	s_cbranch_execz .LBB0_162
	v_add_u32_e32 v6, 0x80, v117
	v_cmp_lt_i32_e32 vcc, s15, v6
	s_movk_i32 s47, 0xff80
	v_cvt_pk_bf16_f32 v4, v4, v5
	v_cndmask_b32_e32 v7, v176, v177, vcc
	v_add_u32_e32 v7, s50, v7
	v_add3_u32 v7, v7, v115, s47
	v_cndmask_b32_e64 v6, v7, v6, s[44:45]
	v_add_u32_e32 v6, s52, v6
	v_ashrrev_i32_e32 v7, 31, v6
	v_lshlrev_b64 v[6:7], 11, v[6:7]
	v_lshl_add_u64 v[6:7], v[82:83], 0, v[6:7]
	v_cvt_pk_bf16_f32 v5, v2, v3
	global_store_dwordx2 v[6:7], v[4:5], off

; __device__ __forceinline__ bfr f2b(float f) { return (bfr)(cvtpk(f, f) & 0xffffu); }
; __device__ __forceinline__ float b2f(bfr b) { return __uint_as_float(((unsigned)b) << 16); }
; __device__ __forceinline__ void store4b(bfr* dst, f32x4 v) { uint2 u; u.x = pk2(v[0], v[1]); u.y = pk2(v[2], v[3]); *(uint2*)dst = u; }
; __device__ __forceinline__ void ph_r7_cb(const P& p, int win, char* smem) {
;     ...
;           const int cur = s & 1, nxt = cur ^ 1, c = c0 + s;
;           bf16x8 sh[2], sl[2], vt[2];
; #pragma unroll
;           for (int ks = 0; ks < 2; ks++) { sh[ks] = *(const bf16x8*)(Sh + (cur * 16 + l15) * CS + 32 * ks + 8 * q4); sl[ks] = *(const bf16x8*)(Sl + (cur * 16 + l15) * CS + 32 * ks + 8 * q4);
;             vt[ks] = *(const bf16x8*)(VT + (cur * 16 + l15) * CS + 32 * ks + 8 * q4); }
;           f32x4 a1 = f32x4{0.f, 0.f, 0.f, 0.f}, a2 = a1;
; #pragma unroll
;           for (int ks = 0; ks < 2; ks++) { a1 = __builtin_amdgcn_mfma_f32_16x16x32_bf16(sh[ks], rb1[u][ks], a1, 0, 0, 0); a2 = __builtin_amdgcn_mfma_f32_16x16x32_bf16(vt[ks], rb2[u][ks], a2, 0, 0, 0); }
; #pragma unroll
;           for (int ks = 0; ks < 2; ks++) a1 = __builtin_amdgcn_mfma_f32_16x16x32_bf16(sl[ks], rb1[u][ks], a1, 0, 0, 0);
;           a1 = a1 + a2;
;           if (w < 4) {
; #pragma unroll
;             for (int jj = 0; jj < 4; jj++) { const bfr hi = f2b(a1[jj]); Sh[(nxt * 16 + 4 * q4 + jj) * CS + 16 * w + l15] = hi; Sl[(nxt * 16 + 4 * q4 + jj) * CS + 16 * w + l15] = f2b(a1[jj] - b2f(hi)); }
;           } else {
;             const int rowy = rowmap(d, b, 64 * c + 16 * (w - 4) + l15);
;             store4b(Y + (size_t)rowy * 1024 + h * 64 + rg * 16 + 4 * q4, a1);
.LBB0_164:
	s_waitcnt vmcnt(0)
	ds_read_b128 v[188:191], v100 offset:9216
	ds_read_b128 v[192:195], v100
	ds_read_b128 v[196:199], v100 offset:64
	ds_read_b128 v[200:203], v100 offset:4608
	ds_read_b128 v[204:207], v100 offset:9280
	ds_read_b128 v[208:211], v100 offset:4672
	s_waitcnt lgkmcnt(0)
	v_mfma_f32_16x16x32_bf16 v[62:65], v[188:191], v[62:65], 0
	v_mfma_f32_16x16x32_bf16 v[84:87], v[192:195], v[58:61], 0
	v_mfma_f32_16x16x32_bf16 v[84:87], v[196:199], v[50:53], v[84:87]
	v_mfma_f32_16x16x32_bf16 v[58:61], v[200:203], v[58:61], v[84:87]
	v_mfma_f32_16x16x32_bf16 v[54:57], v[204:207], v[54:57], v[62:65]
	v_mfma_f32_16x16x32_bf16 v[58:61], v[208:211], v[50:53], v[58:61]
	s_nop 7
	s_nop 1
	v_pk_add_f32 v[50:51], v[60:61], v[56:57]
	v_pk_add_f32 v[52:53], v[58:59], v[54:55]
	s_and_saveexec_b64 s[30:31], s[42:43]
	s_xor_b64 s[30:31], exec, s[30:31]
	s_cbranch_execz .LBB0_166
	v_cndmask_b32_e64 v0, v104, v103, s[44:45]
	v_add_u32_e32 v54, s52, v0
	v_ashrrev_i32_e32 v55, 31, v54
	v_lshlrev_b64 v[54:55], 11, v[54:55]
	v_lshl_add_u64 v[54:55], v[82:83], 0, v[54:55]
	v_cvt_pk_bf16_f32 v52, v52, v53
	v_cvt_pk_bf16_f32 v53, v50, v51
	global_store_dwordx2 v[54:55], v[52:53], off

; __device__ __forceinline__ bfr f2b(float f) { return (bfr)(cvtpk(f, f) & 0xffffu); }
; __device__ __forceinline__ float b2f(bfr b) { return __uint_as_float(((unsigned)b) << 16); }
; __device__ __forceinline__ void store4b(bfr* dst, f32x4 v) { uint2 u; u.x = pk2(v[0], v[1]); u.y = pk2(v[2], v[3]); *(uint2*)dst = u; }
; __device__ __forceinline__ void ph_r7_cb(const P& p, int win, char* smem) {
;     ...
;           const int cur = s & 1, nxt = cur ^ 1, c = c0 + s;
;           bf16x8 sh[2], sl[2], vt[2];
; #pragma unroll
;           for (int ks = 0; ks < 2; ks++) { sh[ks] = *(const bf16x8*)(Sh + (cur * 16 + l15) * CS + 32 * ks + 8 * q4); sl[ks] = *(const bf16x8*)(Sl + (cur * 16 + l15) * CS + 32 * ks + 8 * q4);
;             vt[ks] = *(const bf16x8*)(VT + (cur * 16 + l15) * CS + 32 * ks + 8 * q4); }
;           f32x4 a1 = f32x4{0.f, 0.f, 0.f, 0.f}, a2 = a1;
; #pragma unroll
;           for (int ks = 0; ks < 2; ks++) { a1 = __builtin_amdgcn_mfma_f32_16x16x32_bf16(sh[ks], rb1[u][ks], a1, 0, 0, 0); a2 = __builtin_amdgcn_mfma_f32_16x16x32_bf16(vt[ks], rb2[u][ks], a2, 0, 0, 0); }
; #pragma unroll
;           for (int ks = 0; ks < 2; ks++) a1 = __builtin_amdgcn_mfma_f32_16x16x32_bf16(sl[ks], rb1[u][ks], a1, 0, 0, 0);
;           a1 = a1 + a2;
;           if (w < 4) {
; #pragma unroll
;             for (int jj = 0; jj < 4; jj++) { const bfr hi = f2b(a1[jj]); Sh[(nxt * 16 + 4 * q4 + jj) * CS + 16 * w + l15] = hi; Sl[(nxt * 16 + 4 * q4 + jj) * CS + 16 * w + l15] = f2b(a1[jj] - b2f(hi)); }
;           } else {
;             const int rowy = rowmap(d, b, 64 * c + 16 * (w - 4) + l15);
;             store4b(Y + (size_t)rowy * 1024 + h * 64 + rg * 16 + 4 * q4, a1);
;           }
;           if (s + 1 < 20) { VT[(nxt * 16 + 2 * vp) * CS + vtau] = (bfr)(rv[u] & 0xffff); VT[(nxt * 16 + 2 * vp + 1) * CS + vtau] = (bfr)(rv[u] >> 16); }
;           if (s + 4 < 20) CB_LOAD(u, s + 4)
;           __syncthreads();
.LBB0_168:
	s_or_b64 exec, exec, s[30:31]
	ds_write_b16 v102, v114 offset:11520
	ds_write_b16_d16_hi v89, v114 offset:11664
	s_waitcnt lgkmcnt(0)
	s_barrier
	ds_read_b128 v[188:191], v100 offset:11520
	ds_read_b128 v[192:195], v100 offset:2304
	ds_read_b128 v[196:199], v100 offset:2368
	ds_read_b128 v[200:203], v100 offset:6912
	ds_read_b128 v[204:207], v100 offset:11584
	ds_read_b128 v[208:211], v100 offset:6976
	s_waitcnt lgkmcnt(0)
	v_mfma_f32_16x16x32_bf16 v[46:49], v[188:191], v[46:49], 0
	v_mfma_f32_16x16x32_bf16 v[50:53], v[192:195], v[42:45], 0
	v_mfma_f32_16x16x32_bf16 v[50:53], v[196:199], v[34:37], v[50:53]
	v_mfma_f32_16x16x32_bf16 v[42:45], v[200:203], v[42:45], v[50:53]
	v_mfma_f32_16x16x32_bf16 v[38:41], v[204:207], v[38:41], v[46:49]
	v_mfma_f32_16x16x32_bf16 v[42:45], v[208:211], v[34:37], v[42:45]
	s_nop 7
	s_nop 1
	v_pk_add_f32 v[34:35], v[44:45], v[40:41]
	v_pk_add_f32 v[36:37], v[42:43], v[38:39]
	s_and_saveexec_b64 s[30:31], s[42:43]
	s_xor_b64 s[30:31], exec, s[30:31]
	s_cbranch_execz .LBB0_170
	v_cndmask_b32_e64 v0, v106, v105, s[44:45]
	v_add_u32_e32 v38, s52, v0
	v_ashrrev_i32_e32 v39, 31, v38
	v_lshlrev_b64 v[38:39], 11, v[38:39]
	v_lshl_add_u64 v[38:39], v[82:83], 0, v[38:39]
	v_cvt_pk_bf16_f32 v36, v36, v37
	v_cvt_pk_bf16_f32 v37, v34, v35
	global_store_dwordx2 v[38:39], v[36:37], off

; __device__ __forceinline__ bfr f2b(float f) { return (bfr)(cvtpk(f, f) & 0xffffu); }
; __device__ __forceinline__ float b2f(bfr b) { return __uint_as_float(((unsigned)b) << 16); }
; __device__ __forceinline__ void store4b(bfr* dst, f32x4 v) { uint2 u; u.x = pk2(v[0], v[1]); u.y = pk2(v[2], v[3]); *(uint2*)dst = u; }
; __device__ __forceinline__ void ph_r7_cb(const P& p, int win, char* smem) {
;     ...
;           const int cur = s & 1, nxt = cur ^ 1, c = c0 + s;
;           bf16x8 sh[2], sl[2], vt[2];
; #pragma unroll
;           for (int ks = 0; ks < 2; ks++) { sh[ks] = *(const bf16x8*)(Sh + (cur * 16 + l15) * CS + 32 * ks + 8 * q4); sl[ks] = *(const bf16x8*)(Sl + (cur * 16 + l15) * CS + 32 * ks + 8 * q4);
;             vt[ks] = *(const bf16x8*)(VT + (cur * 16 + l15) * CS + 32 * ks + 8 * q4); }
;           f32x4 a1 = f32x4{0.f, 0.f, 0.f, 0.f}, a2 = a1;
; #pragma unroll
;           for (int ks = 0; ks < 2; ks++) { a1 = __builtin_amdgcn_mfma_f32_16x16x32_bf16(sh[ks], rb1[u][ks], a1, 0, 0, 0); a2 = __builtin_amdgcn_mfma_f32_16x16x32_bf16(vt[ks], rb2[u][ks], a2, 0, 0, 0); }
; #pragma unroll
;           for (int ks = 0; ks < 2; ks++) a1 = __builtin_amdgcn_mfma_f32_16x16x32_bf16(sl[ks], rb1[u][ks], a1, 0, 0, 0);
;           a1 = a1 + a2;
;           if (w < 4) {
; #pragma unroll
;             for (int jj = 0; jj < 4; jj++) { const bfr hi = f2b(a1[jj]); Sh[(nxt * 16 + 4 * q4 + jj) * CS + 16 * w + l15] = hi; Sl[(nxt * 16 + 4 * q4 + jj) * CS + 16 * w + l15] = f2b(a1[jj] - b2f(hi)); }
;           } else {
;             const int rowy = rowmap(d, b, 64 * c + 16 * (w - 4) + l15);
;             store4b(Y + (size_t)rowy * 1024 + h * 64 + rg * 16 + 4 * q4, a1);
;           }
;           if (s + 1 < 20) { VT[(nxt * 16 + 2 * vp) * CS + vtau] = (bfr)(rv[u] & 0xffff); VT[(nxt * 16 + 2 * vp + 1) * CS + vtau] = (bfr)(rv[u] >> 16); }
;           if (s + 4 < 20) CB_LOAD(u, s + 4)
;           __syncthreads();
.LBB0_172:
	s_or_b64 exec, exec, s[30:31]
	ds_write_b16 v102, v81 offset:9216
	ds_write_b16_d16_hi v89, v81 offset:9360
	s_waitcnt lgkmcnt(0)
	s_barrier
	ds_read_b128 v[188:191], v100 offset:9216
	ds_read_b128 v[192:195], v100
	ds_read_b128 v[196:199], v100 offset:64
	ds_read_b128 v[200:203], v100 offset:4608
	ds_read_b128 v[204:207], v100 offset:9280
	ds_read_b128 v[208:211], v100 offset:4672
	s_waitcnt lgkmcnt(0)
	v_mfma_f32_16x16x32_bf16 v[30:33], v[188:191], v[30:33], 0
	v_mfma_f32_16x16x32_bf16 v[34:37], v[192:195], v[26:29], 0
	v_mfma_f32_16x16x32_bf16 v[34:37], v[196:199], v[18:21], v[34:37]
	v_mfma_f32_16x16x32_bf16 v[26:29], v[200:203], v[26:29], v[34:37]
	v_mfma_f32_16x16x32_bf16 v[22:25], v[204:207], v[22:25], v[30:33]
	v_mfma_f32_16x16x32_bf16 v[26:29], v[208:211], v[18:21], v[26:29]
	s_nop 7
	s_nop 1
	v_pk_add_f32 v[18:19], v[28:29], v[24:25]
	v_pk_add_f32 v[20:21], v[26:27], v[22:23]
	s_and_saveexec_b64 s[30:31], s[42:43]
	s_xor_b64 s[30:31], exec, s[30:31]
	s_cbranch_execz .LBB0_174
	v_cndmask_b32_e64 v0, v108, v107, s[44:45]
	v_add_u32_e32 v22, s52, v0
	v_ashrrev_i32_e32 v23, 31, v22
	v_lshlrev_b64 v[22:23], 11, v[22:23]
	v_lshl_add_u64 v[22:23], v[82:83], 0, v[22:23]
	v_cvt_pk_bf16_f32 v20, v20, v21
	v_cvt_pk_bf16_f32 v21, v18, v19
	global_store_dwordx2 v[22:23], v[20:21], off

; __device__ __forceinline__ bfr f2b(float f) { return (bfr)(cvtpk(f, f) & 0xffffu); }
; __device__ __forceinline__ float b2f(bfr b) { return __uint_as_float(((unsigned)b) << 16); }
; __device__ __forceinline__ void store4b(bfr* dst, f32x4 v) { uint2 u; u.x = pk2(v[0], v[1]); u.y = pk2(v[2], v[3]); *(uint2*)dst = u; }
; __device__ __forceinline__ void ph_r7_cb(const P& p, int win, char* smem) {
;     ...
;           const int cur = s & 1, nxt = cur ^ 1, c = c0 + s;
;           bf16x8 sh[2], sl[2], vt[2];
; #pragma unroll
;           for (int ks = 0; ks < 2; ks++) { sh[ks] = *(const bf16x8*)(Sh + (cur * 16 + l15) * CS + 32 * ks + 8 * q4); sl[ks] = *(const bf16x8*)(Sl + (cur * 16 + l15) * CS + 32 * ks + 8 * q4);
;             vt[ks] = *(const bf16x8*)(VT + (cur * 16 + l15) * CS + 32 * ks + 8 * q4); }
;           f32x4 a1 = f32x4{0.f, 0.f, 0.f, 0.f}, a2 = a1;
; #pragma unroll
;           for (int ks = 0; ks < 2; ks++) { a1 = __builtin_amdgcn_mfma_f32_16x16x32_bf16(sh[ks], rb1[u][ks], a1, 0, 0, 0); a2 = __builtin_amdgcn_mfma_f32_16x16x32_bf16(vt[ks], rb2[u][ks], a2, 0, 0, 0); }
; #pragma unroll
;           for (int ks = 0; ks < 2; ks++) a1 = __builtin_amdgcn_mfma_f32_16x16x32_bf16(sl[ks], rb1[u][ks], a1, 0, 0, 0);
;           a1 = a1 + a2;
;           if (w < 4) {
; #pragma unroll
;             for (int jj = 0; jj < 4; jj++) { const bfr hi = f2b(a1[jj]); Sh[(nxt * 16 + 4 * q4 + jj) * CS + 16 * w + l15] = hi; Sl[(nxt * 16 + 4 * q4 + jj) * CS + 16 * w + l15] = f2b(a1[jj] - b2f(hi)); }
;           } else {
;             const int rowy = rowmap(d, b, 64 * c + 16 * (w - 4) + l15);
;             store4b(Y + (size_t)rowy * 1024 + h * 64 + rg * 16 + 4 * q4, a1);
;           }
;           if (s + 1 < 20) { VT[(nxt * 16 + 2 * vp) * CS + vtau] = (bfr)(rv[u] & 0xffff); VT[(nxt * 16 + 2 * vp + 1) * CS + vtau] = (bfr)(rv[u] >> 16); }
;           if (s + 4 < 20) CB_LOAD(u, s + 4)
;           __syncthreads();
.LBB0_176:
	s_or_b64 exec, exec, s[30:31]
	ds_write_b16 v102, v77 offset:11520
	ds_write_b16_d16_hi v89, v77 offset:11664
	s_waitcnt lgkmcnt(0)
	s_barrier
	ds_read_b128 v[188:191], v100 offset:11520
	ds_read_b128 v[192:195], v100 offset:2304
	ds_read_b128 v[196:199], v100 offset:2368
	ds_read_b128 v[200:203], v100 offset:6912
	ds_read_b128 v[204:207], v100 offset:11584
	ds_read_b128 v[208:211], v100 offset:6976
	s_waitcnt lgkmcnt(0)
	v_mfma_f32_16x16x32_bf16 v[14:17], v[188:191], v[14:17], 0
	v_mfma_f32_16x16x32_bf16 v[18:21], v[192:195], v[10:13], 0
	v_mfma_f32_16x16x32_bf16 v[18:21], v[196:199], v[2:5], v[18:21]
	v_mfma_f32_16x16x32_bf16 v[10:13], v[200:203], v[10:13], v[18:21]
	v_mfma_f32_16x16x32_bf16 v[6:9], v[204:207], v[6:9], v[14:17]
	v_mfma_f32_16x16x32_bf16 v[10:13], v[208:211], v[2:5], v[10:13]
	s_nop 7
	s_nop 1
	v_pk_add_f32 v[2:3], v[12:13], v[8:9]
	v_pk_add_f32 v[4:5], v[10:11], v[6:7]
	s_and_saveexec_b64 s[30:31], s[42:43]
	s_xor_b64 s[30:31], exec, s[30:31]
	s_cbranch_execz .LBB0_178
	v_cndmask_b32_e64 v0, v110, v109, s[44:45]
	v_add_u32_e32 v6, s52, v0
	v_ashrrev_i32_e32 v7, 31, v6
	v_lshlrev_b64 v[6:7], 11, v[6:7]
	v_lshl_add_u64 v[6:7], v[82:83], 0, v[6:7]
	v_cvt_pk_bf16_f32 v4, v4, v5
	v_cvt_pk_bf16_f32 v5, v2, v3
	global_store_dwordx2 v[6:7], v[4:5], off
